# previous best + counted per-MFMA LDS waits (lgkmcnt 11..8 and 3..0) in the seven GEMM K-loops instead of one wait per half
# baseline (speedup 1.0000x reference)
.LBB0_303:
	s_setprio 3
	s_and_b32 s1, s0, 0x2000
	s_xor_b32 s8, s1, 0x2000
	s_lshl_b32 s101, s8, 1
	s_add_u32 s101, s101, s100
	s_add_u32 m0, s101, 0x0
	s_nop 0
	global_load_lds_dwordx4 v[184:185], off
	s_add_u32 m0, s101, 0x1000
	v_lshl_add_u64 v[184:185], v[184:185], 0, vcc
	global_load_lds_dwordx4 v[186:187], off
	s_add_u32 m0, s101, 0x2000
	v_lshl_add_u64 v[186:187], v[186:187], 0, vcc
	global_load_lds_dwordx4 v[188:189], off
	s_add_u32 m0, s101, 0x3000
	v_lshl_add_u64 v[188:189], v[188:189], 0, vcc
	global_load_lds_dwordx4 v[190:191], off
	s_add_u32 m0, s101, 0x8000
	v_lshl_add_u64 v[190:191], v[190:191], 0, vcc
	global_load_lds_dwordx4 v[192:193], off
	s_add_u32 m0, s101, 0x9000
	v_lshl_add_u64 v[192:193], v[192:193], 0, vcc
	global_load_lds_dwordx4 v[194:195], off
	s_add_u32 m0, s101, 0xa000
	v_lshl_add_u64 v[194:195], v[194:195], 0, vcc
	global_load_lds_dwordx4 v[196:197], off
	s_add_u32 m0, s101, 0xb000
	v_lshl_add_u64 v[196:197], v[196:197], 0, vcc
	global_load_lds_dwordx4 v[198:199], off
	v_lshl_add_u64 v[198:199], v[198:199], 0, vcc
	s_lshl_b32 s1, s1, 1
	v_add_u32_e32 v82, s1, v86
	v_add_u32_e32 v83, s1, v85
	v_add_u32_e32 v95, v82, v93
	ds_read_b128 v[96:99], v95
	ds_read_b128 v[100:103], v95 offset:2048
	ds_read_b128 v[120:123], v95 offset:4096
	ds_read_b128 v[124:127], v95 offset:6144
	v_add_u32_e32 v95, v83, v93
	ds_read_b128 v[128:131], v95 offset:32768
	ds_read_b128 v[132:135], v95 offset:34816
	ds_read_b128 v[136:139], v95 offset:36864
	ds_read_b128 v[140:143], v95 offset:38912
	v_add_u32_e32 v82, v82, v94
	ds_read_b128 v[200:203], v82
	ds_read_b128 v[204:207], v82 offset:2048
	ds_read_b128 v[208:211], v82 offset:4096
	ds_read_b128 v[212:215], v82 offset:6144
	v_add_u32_e32 v82, v83, v94
	ds_read_b128 v[216:219], v82 offset:32768
	ds_read_b128 v[220:223], v82 offset:34816
	ds_read_b128 v[224:227], v82 offset:36864
	ds_read_b128 v[228:231], v82 offset:38912
	s_setprio 1
	s_waitcnt lgkmcnt(11)
	v_mfma_f32_16x16x32_bf16 v[60:63], v[128:131], v[96:99], v[60:63]
	s_waitcnt lgkmcnt(10)
	v_mfma_f32_16x16x32_bf16 v[56:59], v[132:135], v[96:99], v[56:59]
	s_waitcnt lgkmcnt(9)
	v_mfma_f32_16x16x32_bf16 v[52:55], v[136:139], v[96:99], v[52:55]
	s_waitcnt lgkmcnt(8)
	v_mfma_f32_16x16x32_bf16 v[48:51], v[140:143], v[96:99], v[48:51]
	v_mfma_f32_16x16x32_bf16 v[44:47], v[128:131], v[100:103], v[44:47]
	v_mfma_f32_16x16x32_bf16 v[40:43], v[132:135], v[100:103], v[40:43]
	v_mfma_f32_16x16x32_bf16 v[36:39], v[136:139], v[100:103], v[36:39]
	v_mfma_f32_16x16x32_bf16 v[32:35], v[140:143], v[100:103], v[32:35]
	v_mfma_f32_16x16x32_bf16 v[28:31], v[128:131], v[120:123], v[28:31]
	v_mfma_f32_16x16x32_bf16 v[24:27], v[132:135], v[120:123], v[24:27]
	v_mfma_f32_16x16x32_bf16 v[20:23], v[136:139], v[120:123], v[20:23]
	v_mfma_f32_16x16x32_bf16 v[16:19], v[140:143], v[120:123], v[16:19]
	v_mfma_f32_16x16x32_bf16 v[12:15], v[128:131], v[124:127], v[12:15]
	v_mfma_f32_16x16x32_bf16 v[8:11], v[132:135], v[124:127], v[8:11]
	v_mfma_f32_16x16x32_bf16 v[4:7], v[136:139], v[124:127], v[4:7]
	v_mfma_f32_16x16x32_bf16 v[0:3], v[140:143], v[124:127], v[0:3]
	s_waitcnt lgkmcnt(3)
	v_mfma_f32_16x16x32_bf16 v[60:63], v[216:219], v[200:203], v[60:63]
	s_waitcnt lgkmcnt(2)
	v_mfma_f32_16x16x32_bf16 v[56:59], v[220:223], v[200:203], v[56:59]
	s_waitcnt lgkmcnt(1)
	v_mfma_f32_16x16x32_bf16 v[52:55], v[224:227], v[200:203], v[52:55]
	s_waitcnt lgkmcnt(0)
	v_mfma_f32_16x16x32_bf16 v[48:51], v[228:231], v[200:203], v[48:51]
	v_mfma_f32_16x16x32_bf16 v[44:47], v[216:219], v[204:207], v[44:47]
	v_mfma_f32_16x16x32_bf16 v[40:43], v[220:223], v[204:207], v[40:43]
	v_mfma_f32_16x16x32_bf16 v[36:39], v[224:227], v[204:207], v[36:39]
	v_mfma_f32_16x16x32_bf16 v[32:35], v[228:231], v[204:207], v[32:35]
	v_mfma_f32_16x16x32_bf16 v[28:31], v[216:219], v[208:211], v[28:31]
	v_mfma_f32_16x16x32_bf16 v[24:27], v[220:223], v[208:211], v[24:27]
	v_mfma_f32_16x16x32_bf16 v[20:23], v[224:227], v[208:211], v[20:23]
	v_mfma_f32_16x16x32_bf16 v[16:19], v[228:231], v[208:211], v[16:19]
	v_mfma_f32_16x16x32_bf16 v[12:15], v[216:219], v[212:215], v[12:15]
	v_mfma_f32_16x16x32_bf16 v[8:11], v[220:223], v[212:215], v[8:11]
	v_mfma_f32_16x16x32_bf16 v[4:7], v[224:227], v[212:215], v[4:7]
	v_mfma_f32_16x16x32_bf16 v[0:3], v[228:231], v[212:215], v[0:3]
	s_setprio 0
	s_addk_i32 s0, 0x2000
	s_waitcnt vmcnt(0)
	s_add_u32 s20, s20, 0x80
	s_addc_u32 s21, s21, 0
	s_cmpk_lg_i32 s20, 0x780
	s_waitcnt vmcnt(0)
	s_barrier
	s_cbranch_scc1 .LBB0_303
	ds_read_b128 v[78:81], v89 offset:55296
	ds_read_b128 v[96:99], v89 offset:53248
	ds_read_b128 v[100:103], v89 offset:51200
	ds_read_b128 v[120:123], v89 offset:49152
	ds_read_b128 v[124:127], v90 offset:22528
	ds_read_b128 v[128:131], v90 offset:20480
	ds_read_b128 v[132:135], v90 offset:18432
	ds_read_b128 v[136:139], v90 offset:16384
	s_setprio 1
	s_waitcnt lgkmcnt(0)
	v_mfma_f32_16x16x32_bf16 v[60:63], v[120:123], v[136:139], v[60:63]
	v_mfma_f32_16x16x32_bf16 v[56:59], v[100:103], v[136:139], v[56:59]
	v_mfma_f32_16x16x32_bf16 v[52:55], v[96:99], v[136:139], v[52:55]
	v_mfma_f32_16x16x32_bf16 v[48:51], v[78:81], v[136:139], v[48:51]
	v_mfma_f32_16x16x32_bf16 v[44:47], v[120:123], v[132:135], v[44:47]
	v_mfma_f32_16x16x32_bf16 v[40:43], v[100:103], v[132:135], v[40:43]
	v_mfma_f32_16x16x32_bf16 v[36:39], v[96:99], v[132:135], v[36:39]
	v_mfma_f32_16x16x32_bf16 v[32:35], v[78:81], v[132:135], v[32:35]
	v_mfma_f32_16x16x32_bf16 v[28:31], v[120:123], v[128:131], v[28:31]
	v_mfma_f32_16x16x32_bf16 v[24:27], v[100:103], v[128:131], v[24:27]
	v_mfma_f32_16x16x32_bf16 v[20:23], v[96:99], v[128:131], v[20:23]
	v_mfma_f32_16x16x32_bf16 v[16:19], v[78:81], v[128:131], v[16:19]
	v_mfma_f32_16x16x32_bf16 v[12:15], v[120:123], v[124:127], v[12:15]
	v_mfma_f32_16x16x32_bf16 v[8:11], v[100:103], v[124:127], v[8:11]
	v_mfma_f32_16x16x32_bf16 v[4:7], v[96:99], v[124:127], v[4:7]
	v_mfma_f32_16x16x32_bf16 v[0:3], v[78:81], v[124:127], v[0:3]
	s_setprio 0
	ds_read_b128 v[78:81], v91 offset:16384
	ds_read_b128 v[96:99], v91 offset:18432
	ds_read_b128 v[100:103], v91 offset:20480
	ds_read_b128 v[120:123], v91 offset:22528
	ds_read_b128 v[124:127], v92 offset:49152
	ds_read_b128 v[128:131], v92 offset:51200
	ds_read_b128 v[132:135], v92 offset:53248
	ds_read_b128 v[136:139], v92 offset:55296
	s_setprio 1
	s_waitcnt lgkmcnt(3)
	v_mfma_f32_16x16x32_bf16 v[60:63], v[124:127], v[78:81], v[60:63]
	s_waitcnt lgkmcnt(2)
	v_mfma_f32_16x16x32_bf16 v[56:59], v[128:131], v[78:81], v[56:59]
	s_waitcnt lgkmcnt(1)
	v_mfma_f32_16x16x32_bf16 v[52:55], v[132:135], v[78:81], v[52:55]
	s_waitcnt lgkmcnt(0)
	v_mfma_f32_16x16x32_bf16 v[48:51], v[136:139], v[78:81], v[48:51]
	v_mfma_f32_16x16x32_bf16 v[44:47], v[124:127], v[96:99], v[44:47]
	v_mfma_f32_16x16x32_bf16 v[40:43], v[128:131], v[96:99], v[40:43]
	v_mfma_f32_16x16x32_bf16 v[36:39], v[132:135], v[96:99], v[36:39]
	v_mfma_f32_16x16x32_bf16 v[32:35], v[136:139], v[96:99], v[32:35]
	v_mfma_f32_16x16x32_bf16 v[28:31], v[124:127], v[100:103], v[28:31]
	v_mfma_f32_16x16x32_bf16 v[24:27], v[128:131], v[100:103], v[24:27]
	v_mfma_f32_16x16x32_bf16 v[20:23], v[132:135], v[100:103], v[20:23]
	v_mfma_f32_16x16x32_bf16 v[16:19], v[136:139], v[100:103], v[16:19]
	v_mfma_f32_16x16x32_bf16 v[12:15], v[124:127], v[120:123], v[12:15]
	v_mfma_f32_16x16x32_bf16 v[8:11], v[128:131], v[120:123], v[8:11]
	v_mfma_f32_16x16x32_bf16 v[4:7], v[132:135], v[120:123], v[4:7]
	v_mfma_f32_16x16x32_bf16 v[0:3], v[136:139], v[120:123], v[0:3]
	s_setprio 0
	s_waitcnt vmcnt(0)
	s_cmp_lt_i32 s10, 32
	s_mov_b64 s[0:1], -1
	s_barrier
	s_cbranch_scc1 .LBB0_594
	s_cmp_eq_u32 s10, 32
	s_cselect_b64 s[0:1], -1, 0
	s_and_b64 vcc, exec, s[0:1]
	v_mov_b32_e32 v79, v63
	v_mov_b32_e32 v82, v62
	v_mov_b32_e32 v83, v61
	v_mov_b32_e32 v95, v60
	s_cbranch_vccz .LBB0_323
	v_cmp_nlt_f32_e64 s[8:9], |v60|, s33
	s_and_saveexec_b64 s[12:13], s[8:9]
	s_xor_b64 s[8:9], exec, s[12:13]
	s_cbranch_execz .LBB0_308
	v_add_f32_e64 v78, |v60|, |v60|
	v_mul_f32_e32 v79, 0x3fb8aa3b, v78
	v_rndne_f32_e32 v80, v79
	s_mov_b32 s11, 0x3fb8aa3b
	v_sub_f32_e32 v81, v79, v80
	v_fma_f32 v79, v78, s11, -v79
	v_fmac_f32_e32 v79, 0x32a5705f, v78
	v_add_f32_e32 v79, v81, v79
	v_cvt_i32_f32_e32 v80, v80
	v_exp_f32_e32 v79, v79
	s_mov_b32 s11, 0xc2ce8ed0
	v_cmp_ngt_f32_e32 vcc, s11, v78
	s_mov_b32 s11, 0x42b17218
	v_ldexp_f32 v79, v79, v80
	v_cndmask_b32_e32 v79, 0, v79, vcc
	v_cmp_nlt_f32_e32 vcc, s11, v78
	s_nop 1
	v_cndmask_b32_e32 v78, v112, v79, vcc
	v_add_f32_e32 v78, 1.0, v78
	v_rcp_f32_e32 v78, v78
	s_nop 0
	v_fma_f32 v78, v78, -2.0, 1.0

.LBB0_882:
	s_setprio 3
	s_and_b32 s6, s0, 0x2000
	s_xor_b32 s8, s6, 0x2000
	s_lshl_b32 s101, s8, 1
	s_add_u32 s101, s101, s100
	s_add_u32 m0, s101, 0x0
	s_nop 0
	global_load_lds_dwordx4 v[184:185], off
	s_add_u32 m0, s101, 0x1000
	v_lshl_add_u64 v[184:185], v[184:185], 0, vcc
	global_load_lds_dwordx4 v[186:187], off
	s_add_u32 m0, s101, 0x2000
	v_lshl_add_u64 v[186:187], v[186:187], 0, vcc
	global_load_lds_dwordx4 v[188:189], off
	s_add_u32 m0, s101, 0x3000
	v_lshl_add_u64 v[188:189], v[188:189], 0, vcc
	global_load_lds_dwordx4 v[190:191], off
	s_add_u32 m0, s101, 0x8000
	v_lshl_add_u64 v[190:191], v[190:191], 0, vcc
	global_load_lds_dwordx4 v[192:193], off
	s_add_u32 m0, s101, 0x9000
	v_lshl_add_u64 v[192:193], v[192:193], 0, vcc
	global_load_lds_dwordx4 v[194:195], off
	s_add_u32 m0, s101, 0xa000
	v_lshl_add_u64 v[194:195], v[194:195], 0, vcc
	global_load_lds_dwordx4 v[196:197], off
	s_add_u32 m0, s101, 0xb000
	v_lshl_add_u64 v[196:197], v[196:197], 0, vcc
	global_load_lds_dwordx4 v[198:199], off
	v_lshl_add_u64 v[198:199], v[198:199], 0, vcc
	s_lshl_b32 s6, s6, 1
	v_add_u32_e32 v102, s6, v90
	v_add_u32_e32 v103, s6, v71
	v_add_u32_e32 v128, v102, v96
	v_add_u32_e32 v144, v103, v96
	ds_read_b128 v[98:101], v128
	ds_read_b128 v[120:123], v128 offset:2048
	ds_read_b128 v[124:127], v128 offset:4096
	ds_read_b128 v[128:131], v128 offset:6144
	ds_read_b128 v[132:135], v144 offset:32768
	ds_read_b128 v[136:139], v144 offset:34816
	ds_read_b128 v[140:143], v144 offset:36864
	ds_read_b128 v[144:147], v144 offset:38912
	v_add_u32_e32 v102, v102, v97
	ds_read_b128 v[200:203], v102
	ds_read_b128 v[204:207], v102 offset:2048
	ds_read_b128 v[208:211], v102 offset:4096
	ds_read_b128 v[212:215], v102 offset:6144
	v_add_u32_e32 v102, v103, v97
	ds_read_b128 v[216:219], v102 offset:32768
	ds_read_b128 v[220:223], v102 offset:34816
	ds_read_b128 v[224:227], v102 offset:36864
	ds_read_b128 v[228:231], v102 offset:38912
	s_setprio 1
	s_waitcnt lgkmcnt(11)
	v_mfma_f32_16x16x32_bf16 v[60:63], v[132:135], v[98:101], v[60:63]
	s_waitcnt lgkmcnt(10)
	v_mfma_f32_16x16x32_bf16 v[56:59], v[136:139], v[98:101], v[56:59]
	s_waitcnt lgkmcnt(9)
	v_mfma_f32_16x16x32_bf16 v[52:55], v[140:143], v[98:101], v[52:55]
	s_waitcnt lgkmcnt(8)
	v_mfma_f32_16x16x32_bf16 v[48:51], v[144:147], v[98:101], v[48:51]
	v_mfma_f32_16x16x32_bf16 v[44:47], v[132:135], v[120:123], v[44:47]
	v_mfma_f32_16x16x32_bf16 v[40:43], v[136:139], v[120:123], v[40:43]
	v_mfma_f32_16x16x32_bf16 v[36:39], v[140:143], v[120:123], v[36:39]
	v_mfma_f32_16x16x32_bf16 v[32:35], v[144:147], v[120:123], v[32:35]
	v_mfma_f32_16x16x32_bf16 v[28:31], v[132:135], v[124:127], v[28:31]
	v_mfma_f32_16x16x32_bf16 v[24:27], v[136:139], v[124:127], v[24:27]
	v_mfma_f32_16x16x32_bf16 v[20:23], v[140:143], v[124:127], v[20:23]
	v_mfma_f32_16x16x32_bf16 v[16:19], v[144:147], v[124:127], v[16:19]
	v_mfma_f32_16x16x32_bf16 v[12:15], v[132:135], v[128:131], v[12:15]
	v_mfma_f32_16x16x32_bf16 v[8:11], v[136:139], v[128:131], v[8:11]
	v_mfma_f32_16x16x32_bf16 v[4:7], v[140:143], v[128:131], v[4:7]
	v_mfma_f32_16x16x32_bf16 v[0:3], v[144:147], v[128:131], v[0:3]
	s_waitcnt lgkmcnt(3)
	v_mfma_f32_16x16x32_bf16 v[60:63], v[216:219], v[200:203], v[60:63]
	s_waitcnt lgkmcnt(2)
	v_mfma_f32_16x16x32_bf16 v[56:59], v[220:223], v[200:203], v[56:59]
	s_waitcnt lgkmcnt(1)
	v_mfma_f32_16x16x32_bf16 v[52:55], v[224:227], v[200:203], v[52:55]
	s_waitcnt lgkmcnt(0)
	v_mfma_f32_16x16x32_bf16 v[48:51], v[228:231], v[200:203], v[48:51]
	v_mfma_f32_16x16x32_bf16 v[44:47], v[216:219], v[204:207], v[44:47]
	v_mfma_f32_16x16x32_bf16 v[40:43], v[220:223], v[204:207], v[40:43]
	v_mfma_f32_16x16x32_bf16 v[36:39], v[224:227], v[204:207], v[36:39]
	v_mfma_f32_16x16x32_bf16 v[32:35], v[228:231], v[204:207], v[32:35]
	v_mfma_f32_16x16x32_bf16 v[28:31], v[216:219], v[208:211], v[28:31]
	v_mfma_f32_16x16x32_bf16 v[24:27], v[220:223], v[208:211], v[24:27]
	v_mfma_f32_16x16x32_bf16 v[20:23], v[224:227], v[208:211], v[20:23]
	v_mfma_f32_16x16x32_bf16 v[16:19], v[228:231], v[208:211], v[16:19]
	v_mfma_f32_16x16x32_bf16 v[12:15], v[216:219], v[212:215], v[12:15]
	v_mfma_f32_16x16x32_bf16 v[8:11], v[220:223], v[212:215], v[8:11]
	v_mfma_f32_16x16x32_bf16 v[4:7], v[224:227], v[212:215], v[4:7]
	v_mfma_f32_16x16x32_bf16 v[0:3], v[228:231], v[212:215], v[0:3]
	s_setprio 0
	s_waitcnt vmcnt(0)
	s_add_u32 s36, s36, 0x80
	s_addc_u32 s37, s37, 0
	s_addk_i32 s0, 0x2000
	s_cmpk_lg_i32 s36, 0x780
	s_waitcnt vmcnt(0)
	s_barrier
	s_cbranch_scc1 .LBB0_882
	ds_read_b128 v[86:89], v92 offset:16384
	ds_read_b128 v[98:101], v92 offset:18432
	ds_read_b128 v[120:123], v92 offset:20480
	ds_read_b128 v[124:127], v92 offset:22528
	ds_read_b128 v[128:131], v93 offset:49152
	ds_read_b128 v[132:135], v93 offset:51200
	ds_read_b128 v[136:139], v93 offset:53248
	ds_read_b128 v[140:143], v93 offset:55296
	s_setprio 1
	s_waitcnt lgkmcnt(3)
	v_mfma_f32_16x16x32_bf16 v[60:63], v[128:131], v[86:89], v[60:63]
	s_waitcnt lgkmcnt(2)
	v_mfma_f32_16x16x32_bf16 v[56:59], v[132:135], v[86:89], v[56:59]
	s_waitcnt lgkmcnt(1)
	v_mfma_f32_16x16x32_bf16 v[52:55], v[136:139], v[86:89], v[52:55]
	s_waitcnt lgkmcnt(0)
	v_mfma_f32_16x16x32_bf16 v[48:51], v[140:143], v[86:89], v[48:51]
	v_mfma_f32_16x16x32_bf16 v[40:43], v[132:135], v[98:101], v[40:43]
	v_mfma_f32_16x16x32_bf16 v[36:39], v[136:139], v[98:101], v[36:39]
	v_mfma_f32_16x16x32_bf16 v[32:35], v[140:143], v[98:101], v[32:35]
	v_mfma_f32_16x16x32_bf16 v[20:23], v[136:139], v[120:123], v[20:23]
	v_mfma_f32_16x16x32_bf16 v[16:19], v[140:143], v[120:123], v[16:19]
	v_mfma_f32_16x16x32_bf16 v[0:3], v[140:143], v[124:127], v[0:3]
	v_mfma_f32_16x16x32_bf16 v[86:89], v[128:131], v[98:101], v[44:47]
	v_mfma_f32_16x16x32_bf16 v[98:101], v[128:131], v[120:123], v[28:31]
	v_mfma_f32_16x16x32_bf16 v[144:147], v[132:135], v[120:123], v[24:27]
	v_mfma_f32_16x16x32_bf16 v[120:123], v[128:131], v[124:127], v[12:15]
	v_mfma_f32_16x16x32_bf16 v[128:131], v[132:135], v[124:127], v[8:11]
	v_mfma_f32_16x16x32_bf16 v[132:135], v[136:139], v[124:127], v[4:7]
	s_setprio 0
	s_nop 1
	ds_read_b128 v[4:7], v94 offset:16384
	ds_read_b128 v[8:11], v94 offset:18432
	ds_read_b128 v[124:127], v94 offset:20480
	ds_read_b128 v[136:139], v94 offset:22528
	ds_read_b128 v[140:143], v95 offset:49152
	ds_read_b128 v[148:151], v95 offset:51200
	ds_read_b128 v[152:155], v95 offset:53248
	ds_read_b128 v[156:159], v95 offset:55296
	s_setprio 1
	s_waitcnt lgkmcnt(3)
	v_mfma_f32_16x16x32_bf16 v[60:63], v[140:143], v[4:7], v[60:63]
	s_waitcnt lgkmcnt(2)
	v_mfma_f32_16x16x32_bf16 v[44:47], v[148:151], v[4:7], v[56:59]
	s_waitcnt lgkmcnt(1)
	v_mfma_f32_16x16x32_bf16 v[28:31], v[152:155], v[4:7], v[52:55]
	s_waitcnt lgkmcnt(0)
	v_mfma_f32_16x16x32_bf16 v[12:15], v[156:159], v[4:7], v[48:51]
	v_mfma_f32_16x16x32_bf16 v[56:59], v[140:143], v[8:11], v[86:89]
	v_mfma_f32_16x16x32_bf16 v[40:43], v[148:151], v[8:11], v[40:43]
	v_mfma_f32_16x16x32_bf16 v[24:27], v[152:155], v[8:11], v[36:39]
	v_mfma_f32_16x16x32_bf16 v[8:11], v[156:159], v[8:11], v[32:35]
	v_mfma_f32_16x16x32_bf16 v[52:55], v[140:143], v[124:127], v[98:101]
	v_mfma_f32_16x16x32_bf16 v[36:39], v[148:151], v[124:127], v[144:147]
	v_mfma_f32_16x16x32_bf16 v[20:23], v[152:155], v[124:127], v[20:23]
	v_mfma_f32_16x16x32_bf16 v[4:7], v[156:159], v[124:127], v[16:19]
	v_mfma_f32_16x16x32_bf16 v[48:51], v[140:143], v[136:139], v[120:123]
	v_mfma_f32_16x16x32_bf16 v[32:35], v[148:151], v[136:139], v[128:131]
	v_mfma_f32_16x16x32_bf16 v[16:19], v[152:155], v[136:139], v[132:135]
	v_mfma_f32_16x16x32_bf16 v[0:3], v[156:159], v[136:139], v[0:3]
	s_setprio 0
	s_waitcnt vmcnt(0)
	s_cmpk_gt_i32 s1, 0x7f
	s_barrier
	s_cbranch_scc0 .LBB0_885
	s_add_i32 s0, s24, 0xffffc000
	s_lshr_b32 s0, s0, 8
	v_readlane_b32 s6, v180, 24
	s_add_i32 s6, s0, s6
	s_and_b32 s10, s24, 0x80
	s_lshl_b64 s[8:9], s[6:7], 8
	v_readlane_b32 s36, v182, 19
	s_or_b32 s8, s8, s10
	s_mov_b64 s[10:11], 0
	v_readlane_b32 s37, v182, 20
	s_branch .LBB0_886

.LBB0_895:
	s_setprio 3
	s_and_b32 s0, s10, 0x2000
	s_xor_b32 s1, s0, 0x2000
	s_lshl_b32 s101, s1, 1
	s_add_u32 s101, s101, s100
	s_add_u32 m0, s101, 0x0
	s_nop 0
	global_load_lds_dwordx4 v[184:185], off
	s_add_u32 m0, s101, 0x1000
	v_lshl_add_u64 v[184:185], v[184:185], 0, vcc
	global_load_lds_dwordx4 v[186:187], off
	s_add_u32 m0, s101, 0x2000
	v_lshl_add_u64 v[186:187], v[186:187], 0, vcc
	global_load_lds_dwordx4 v[188:189], off
	s_add_u32 m0, s101, 0x3000
	v_lshl_add_u64 v[188:189], v[188:189], 0, vcc
	global_load_lds_dwordx4 v[190:191], off
	s_add_u32 m0, s101, 0x8000
	v_lshl_add_u64 v[190:191], v[190:191], 0, vcc
	global_load_lds_dwordx4 v[192:193], off
	s_add_u32 m0, s101, 0x9000
	v_lshl_add_u64 v[192:193], v[192:193], 0, vcc
	global_load_lds_dwordx4 v[194:195], off
	s_add_u32 m0, s101, 0xa000
	v_lshl_add_u64 v[194:195], v[194:195], 0, vcc
	global_load_lds_dwordx4 v[196:197], off
	s_add_u32 m0, s101, 0xb000
	v_lshl_add_u64 v[196:197], v[196:197], 0, vcc
	global_load_lds_dwordx4 v[198:199], off
	v_lshl_add_u64 v[198:199], v[198:199], 0, vcc
	s_lshl_b32 s0, s0, 1
	v_add_u32_e32 v68, s0, v120
	v_add_u32_e32 v102, s0, v121
	v_add_u32_e32 v98, v68, v133
	v_add_u32_e32 v103, v102, v133
	ds_read_b128 v[86:89], v98
	ds_read_b128 v[90:93], v98 offset:2048
	ds_read_b128 v[94:97], v98 offset:4096
	ds_read_b128 v[98:101], v98 offset:6144
	ds_read_b128 v[144:147], v103 offset:32768
	ds_read_b128 v[148:151], v103 offset:34816
	ds_read_b128 v[152:155], v103 offset:36864
	ds_read_b128 v[156:159], v103 offset:38912
	v_add_u32_e32 v68, v68, v134
	ds_read_b128 v[200:203], v68
	ds_read_b128 v[204:207], v68 offset:2048
	ds_read_b128 v[208:211], v68 offset:4096
	ds_read_b128 v[212:215], v68 offset:6144
	v_add_u32_e32 v68, v102, v134
	ds_read_b128 v[216:219], v68 offset:32768
	ds_read_b128 v[220:223], v68 offset:34816
	ds_read_b128 v[224:227], v68 offset:36864
	ds_read_b128 v[228:231], v68 offset:38912
	s_setprio 1
	s_waitcnt lgkmcnt(11)
	v_mfma_f32_16x16x32_bf16 v[60:63], v[86:89], v[144:147], v[60:63]
	s_waitcnt lgkmcnt(10)
	v_mfma_f32_16x16x32_bf16 v[56:59], v[86:89], v[148:151], v[56:59]
	s_waitcnt lgkmcnt(9)
	v_mfma_f32_16x16x32_bf16 v[52:55], v[86:89], v[152:155], v[52:55]
	s_waitcnt lgkmcnt(8)
	v_mfma_f32_16x16x32_bf16 v[48:51], v[86:89], v[156:159], v[48:51]
	v_mfma_f32_16x16x32_bf16 v[44:47], v[90:93], v[144:147], v[44:47]
	v_mfma_f32_16x16x32_bf16 v[40:43], v[90:93], v[148:151], v[40:43]
	v_mfma_f32_16x16x32_bf16 v[36:39], v[90:93], v[152:155], v[36:39]
	v_mfma_f32_16x16x32_bf16 v[32:35], v[90:93], v[156:159], v[32:35]
	v_mfma_f32_16x16x32_bf16 v[28:31], v[94:97], v[144:147], v[28:31]
	v_mfma_f32_16x16x32_bf16 v[24:27], v[94:97], v[148:151], v[24:27]
	v_mfma_f32_16x16x32_bf16 v[20:23], v[94:97], v[152:155], v[20:23]
	v_mfma_f32_16x16x32_bf16 v[16:19], v[94:97], v[156:159], v[16:19]
	v_mfma_f32_16x16x32_bf16 v[12:15], v[98:101], v[144:147], v[12:15]
	v_mfma_f32_16x16x32_bf16 v[8:11], v[98:101], v[148:151], v[8:11]
	v_mfma_f32_16x16x32_bf16 v[4:7], v[98:101], v[152:155], v[4:7]
	v_mfma_f32_16x16x32_bf16 v[0:3], v[98:101], v[156:159], v[0:3]
	s_waitcnt lgkmcnt(3)
	v_mfma_f32_16x16x32_bf16 v[60:63], v[200:203], v[216:219], v[60:63]
	s_waitcnt lgkmcnt(2)
	v_mfma_f32_16x16x32_bf16 v[56:59], v[200:203], v[220:223], v[56:59]
	s_waitcnt lgkmcnt(1)
	v_mfma_f32_16x16x32_bf16 v[52:55], v[200:203], v[224:227], v[52:55]
	s_waitcnt lgkmcnt(0)
	v_mfma_f32_16x16x32_bf16 v[48:51], v[200:203], v[228:231], v[48:51]
	v_mfma_f32_16x16x32_bf16 v[44:47], v[204:207], v[216:219], v[44:47]
	v_mfma_f32_16x16x32_bf16 v[40:43], v[204:207], v[220:223], v[40:43]
	v_mfma_f32_16x16x32_bf16 v[36:39], v[204:207], v[224:227], v[36:39]
	v_mfma_f32_16x16x32_bf16 v[32:35], v[204:207], v[228:231], v[32:35]
	v_mfma_f32_16x16x32_bf16 v[28:31], v[208:211], v[216:219], v[28:31]
	v_mfma_f32_16x16x32_bf16 v[24:27], v[208:211], v[220:223], v[24:27]
	v_mfma_f32_16x16x32_bf16 v[20:23], v[208:211], v[224:227], v[20:23]
	v_mfma_f32_16x16x32_bf16 v[16:19], v[208:211], v[228:231], v[16:19]
	v_mfma_f32_16x16x32_bf16 v[12:15], v[212:215], v[216:219], v[12:15]
	v_mfma_f32_16x16x32_bf16 v[8:11], v[212:215], v[220:223], v[8:11]
	v_mfma_f32_16x16x32_bf16 v[4:7], v[212:215], v[224:227], v[4:7]
	v_mfma_f32_16x16x32_bf16 v[0:3], v[212:215], v[228:231], v[0:3]
	s_setprio 0
	s_addk_i32 s10, 0x2000
	s_waitcnt vmcnt(0)
	s_add_u32 s36, s36, 0x80
	s_addc_u32 s37, s37, 0
	s_cmpk_lg_i32 s36, 0x780
	s_waitcnt vmcnt(0)
	s_barrier
	s_cbranch_scc1 .LBB0_895
	ds_read_b128 v[82:85], v122 offset:55296
	ds_read_b128 v[86:89], v122 offset:53248
	ds_read_b128 v[90:93], v122 offset:51200
	ds_read_b128 v[94:97], v122 offset:49152
	ds_read_b128 v[98:101], v123 offset:22528
	ds_read_b128 v[144:147], v123 offset:20480
	ds_read_b128 v[148:151], v123 offset:18432
	ds_read_b128 v[152:155], v123 offset:16384
	s_setprio 1
	s_waitcnt lgkmcnt(0)
	v_mfma_f32_16x16x32_bf16 v[60:63], v[152:155], v[94:97], v[60:63]
	v_mfma_f32_16x16x32_bf16 v[52:55], v[152:155], v[86:89], v[52:55]
	v_mfma_f32_16x16x32_bf16 v[48:51], v[152:155], v[82:85], v[48:51]
	v_mfma_f32_16x16x32_bf16 v[44:47], v[148:151], v[94:97], v[44:47]
	v_mfma_f32_16x16x32_bf16 v[40:43], v[148:151], v[90:93], v[40:43]
	v_mfma_f32_16x16x32_bf16 v[36:39], v[148:151], v[86:89], v[36:39]
	v_mfma_f32_16x16x32_bf16 v[32:35], v[148:151], v[82:85], v[32:35]
	v_mfma_f32_16x16x32_bf16 v[4:7], v[98:101], v[86:89], v[4:7]
	v_mfma_f32_16x16x32_bf16 v[156:159], v[152:155], v[90:93], v[56:59]
	v_mfma_f32_16x16x32_bf16 v[148:151], v[144:147], v[94:97], v[28:31]
	v_mfma_f32_16x16x32_bf16 v[152:155], v[144:147], v[90:93], v[24:27]
	v_mfma_f32_16x16x32_bf16 v[160:163], v[144:147], v[86:89], v[20:23]
	v_mfma_f32_16x16x32_bf16 v[144:147], v[144:147], v[82:85], v[16:19]
	v_mfma_f32_16x16x32_bf16 v[94:97], v[98:101], v[94:97], v[12:15]
	v_mfma_f32_16x16x32_bf16 v[90:93], v[98:101], v[90:93], v[8:11]
	v_mfma_f32_16x16x32_bf16 v[82:85], v[98:101], v[82:85], v[0:3]
	s_setprio 0
	s_nop 1
	ds_read_b128 v[0:3], v124 offset:16384
	ds_read_b128 v[8:11], v124 offset:18432
	ds_read_b128 v[12:15], v124 offset:20480
	ds_read_b128 v[86:89], v124 offset:22528
	ds_read_b128 v[98:101], v125 offset:49152
	ds_read_b128 v[164:167], v125 offset:51200
	ds_read_b128 v[168:171], v125 offset:53248
	ds_read_b128 v[172:175], v125 offset:55296
	s_setprio 1
	s_waitcnt lgkmcnt(3)
	v_mfma_f32_16x16x32_bf16 v[56:59], v[0:3], v[98:101], v[60:63]
	s_waitcnt lgkmcnt(2)
	v_mfma_f32_16x16x32_bf16 v[60:63], v[0:3], v[164:167], v[156:159]
	s_waitcnt lgkmcnt(1)
	v_mfma_f32_16x16x32_bf16 v[24:27], v[0:3], v[168:171], v[52:55]
	s_waitcnt lgkmcnt(0)
	v_mfma_f32_16x16x32_bf16 v[28:31], v[0:3], v[172:175], v[48:51]
	v_mfma_f32_16x16x32_bf16 v[52:55], v[8:11], v[98:101], v[44:47]
	v_mfma_f32_16x16x32_bf16 v[48:51], v[8:11], v[164:167], v[40:43]
	v_mfma_f32_16x16x32_bf16 v[16:19], v[8:11], v[168:171], v[36:39]
	v_mfma_f32_16x16x32_bf16 v[20:23], v[8:11], v[172:175], v[32:35]
	v_mfma_f32_16x16x32_bf16 v[40:43], v[12:15], v[98:101], v[148:151]
	v_mfma_f32_16x16x32_bf16 v[44:47], v[12:15], v[164:167], v[152:155]
	v_mfma_f32_16x16x32_bf16 v[8:11], v[12:15], v[168:171], v[160:163]
	v_mfma_f32_16x16x32_bf16 v[12:15], v[12:15], v[172:175], v[144:147]
	v_mfma_f32_16x16x32_bf16 v[32:35], v[86:89], v[98:101], v[94:97]
	v_mfma_f32_16x16x32_bf16 v[36:39], v[86:89], v[164:167], v[90:93]
	v_mfma_f32_16x16x32_bf16 v[0:3], v[86:89], v[168:171], v[4:7]
	v_mfma_f32_16x16x32_bf16 v[4:7], v[86:89], v[172:175], v[82:85]
	s_setprio 0
	s_waitcnt vmcnt(0)
	s_cmpk_lt_i32 s9, 0x80
	s_cselect_b64 s[42:43], -1, 0
	s_cmpk_gt_i32 s9, 0x7f
	s_mov_b64 s[0:1], -1
	s_barrier
	s_cbranch_scc0 .LBB0_904
	s_and_b32 s10, s20, 0x80
	s_cbranch_execz .LBB0_905

.LBB0_1239:
	s_setprio 3
	s_and_b32 s9, s8, 0x2000
	s_xor_b32 s18, s9, 0x2000
	s_lshl_b32 s101, s18, 1
	s_add_u32 s101, s101, s100
	s_add_u32 m0, s101, 0x0
	s_nop 0
	global_load_lds_dwordx4 v[184:185], off
	s_add_u32 m0, s101, 0x1000
	v_lshl_add_u64 v[184:185], v[184:185], 0, vcc
	global_load_lds_dwordx4 v[186:187], off
	s_add_u32 m0, s101, 0x2000
	v_lshl_add_u64 v[186:187], v[186:187], 0, vcc
	global_load_lds_dwordx4 v[188:189], off
	s_add_u32 m0, s101, 0x3000
	v_lshl_add_u64 v[188:189], v[188:189], 0, vcc
	global_load_lds_dwordx4 v[190:191], off
	s_add_u32 m0, s101, 0x8000
	v_lshl_add_u64 v[190:191], v[190:191], 0, vcc
	global_load_lds_dwordx4 v[192:193], off
	s_add_u32 m0, s101, 0x9000
	v_lshl_add_u64 v[192:193], v[192:193], 0, vcc
	global_load_lds_dwordx4 v[194:195], off
	s_add_u32 m0, s101, 0xa000
	v_lshl_add_u64 v[194:195], v[194:195], 0, vcc
	global_load_lds_dwordx4 v[196:197], off
	s_add_u32 m0, s101, 0xb000
	v_lshl_add_u64 v[196:197], v[196:197], 0, vcc
	global_load_lds_dwordx4 v[198:199], off
	v_lshl_add_u64 v[198:199], v[198:199], 0, vcc
	s_lshl_b32 s9, s9, 1
	v_add_u32_e32 v136, s9, v84
	v_add_u32_e32 v137, s9, v83
	v_add_u32_e32 v100, v136, v86
	v_add_u32_e32 v132, v137, v86
	ds_read_b128 v[88:91], v100
	ds_read_b128 v[92:95], v100 offset:2048
	ds_read_b128 v[96:99], v100 offset:4096
	ds_read_b128 v[100:103], v100 offset:6144
	ds_read_b128 v[120:123], v132 offset:32768
	ds_read_b128 v[124:127], v132 offset:34816
	ds_read_b128 v[128:131], v132 offset:36864
	ds_read_b128 v[132:135], v132 offset:38912
	v_add_u32_e32 v232, v136, v87
	v_add_u32_e32 v233, v137, v87
	ds_read_b128 v[200:203], v232
	ds_read_b128 v[204:207], v232 offset:2048
	ds_read_b128 v[208:211], v232 offset:4096
	ds_read_b128 v[212:215], v232 offset:6144
	ds_read_b128 v[216:219], v233 offset:32768
	ds_read_b128 v[220:223], v233 offset:34816
	ds_read_b128 v[224:227], v233 offset:36864
	ds_read_b128 v[228:231], v233 offset:38912
	s_setprio 1
	s_waitcnt lgkmcnt(11)
	v_mfma_f32_16x16x32_bf16 v[60:63], v[120:123], v[88:91], v[60:63]
	s_waitcnt lgkmcnt(10)
	v_mfma_f32_16x16x32_bf16 v[56:59], v[124:127], v[88:91], v[56:59]
	s_waitcnt lgkmcnt(9)
	v_mfma_f32_16x16x32_bf16 v[52:55], v[128:131], v[88:91], v[52:55]
	s_waitcnt lgkmcnt(8)
	v_mfma_f32_16x16x32_bf16 v[48:51], v[132:135], v[88:91], v[48:51]
	v_mfma_f32_16x16x32_bf16 v[44:47], v[120:123], v[92:95], v[44:47]
	v_mfma_f32_16x16x32_bf16 v[40:43], v[124:127], v[92:95], v[40:43]
	v_mfma_f32_16x16x32_bf16 v[36:39], v[128:131], v[92:95], v[36:39]
	v_mfma_f32_16x16x32_bf16 v[32:35], v[132:135], v[92:95], v[32:35]
	v_mfma_f32_16x16x32_bf16 v[28:31], v[120:123], v[96:99], v[28:31]
	v_mfma_f32_16x16x32_bf16 v[24:27], v[124:127], v[96:99], v[24:27]
	v_mfma_f32_16x16x32_bf16 v[20:23], v[128:131], v[96:99], v[20:23]
	v_mfma_f32_16x16x32_bf16 v[16:19], v[132:135], v[96:99], v[16:19]
	v_mfma_f32_16x16x32_bf16 v[12:15], v[120:123], v[100:103], v[12:15]
	v_mfma_f32_16x16x32_bf16 v[8:11], v[124:127], v[100:103], v[8:11]
	v_mfma_f32_16x16x32_bf16 v[4:7], v[128:131], v[100:103], v[4:7]
	v_mfma_f32_16x16x32_bf16 v[0:3], v[132:135], v[100:103], v[0:3]
	s_waitcnt lgkmcnt(3)
	v_mfma_f32_16x16x32_bf16 v[60:63], v[216:219], v[200:203], v[60:63]
	s_waitcnt lgkmcnt(2)
	v_mfma_f32_16x16x32_bf16 v[56:59], v[220:223], v[200:203], v[56:59]
	s_waitcnt lgkmcnt(1)
	v_mfma_f32_16x16x32_bf16 v[52:55], v[224:227], v[200:203], v[52:55]
	s_waitcnt lgkmcnt(0)
	v_mfma_f32_16x16x32_bf16 v[48:51], v[228:231], v[200:203], v[48:51]
	v_mfma_f32_16x16x32_bf16 v[44:47], v[216:219], v[204:207], v[44:47]
	v_mfma_f32_16x16x32_bf16 v[40:43], v[220:223], v[204:207], v[40:43]
	v_mfma_f32_16x16x32_bf16 v[36:39], v[224:227], v[204:207], v[36:39]
	v_mfma_f32_16x16x32_bf16 v[32:35], v[228:231], v[204:207], v[32:35]
	v_mfma_f32_16x16x32_bf16 v[28:31], v[216:219], v[208:211], v[28:31]
	v_mfma_f32_16x16x32_bf16 v[24:27], v[220:223], v[208:211], v[24:27]
	v_mfma_f32_16x16x32_bf16 v[20:23], v[224:227], v[208:211], v[20:23]
	v_mfma_f32_16x16x32_bf16 v[16:19], v[228:231], v[208:211], v[16:19]
	v_mfma_f32_16x16x32_bf16 v[12:15], v[216:219], v[212:215], v[12:15]
	v_mfma_f32_16x16x32_bf16 v[8:11], v[220:223], v[212:215], v[8:11]
	v_mfma_f32_16x16x32_bf16 v[4:7], v[224:227], v[212:215], v[4:7]
	v_mfma_f32_16x16x32_bf16 v[0:3], v[228:231], v[212:215], v[0:3]
	s_setprio 0
	s_waitcnt vmcnt(0)
	s_add_u32 s20, s20, 0x80
	s_addc_u32 s21, s21, 0
	s_addk_i32 s8, 0x2000
	s_cmp_lg_u32 s1, s20
	s_waitcnt vmcnt(0)
	s_barrier
	s_cbranch_scc1 .LBB0_1239
	s_lshl_b32 s1, s36, 14
	s_addk_i32 s1, 0x4000
	s_and_b32 s1, s1, 0x4000
	v_add_u32_e32 v132, s1, v84
	v_add_u32_e32 v133, s1, v83
	v_add_u32_e32 v96, v132, v86
	v_add_u32_e32 v128, v133, v86
	ds_read_b128 v[78:81], v96
	ds_read_b128 v[88:91], v96 offset:2048
	ds_read_b128 v[92:95], v96 offset:4096
	ds_read_b128 v[96:99], v96 offset:6144
	ds_read_b128 v[100:103], v128 offset:32768
	ds_read_b128 v[120:123], v128 offset:34816
	ds_read_b128 v[124:127], v128 offset:36864
	ds_read_b128 v[128:131], v128 offset:38912
	s_setprio 1
	s_waitcnt lgkmcnt(3)
	v_mfma_f32_16x16x32_bf16 v[60:63], v[100:103], v[78:81], v[60:63]
	s_waitcnt lgkmcnt(2)
	v_mfma_f32_16x16x32_bf16 v[56:59], v[120:123], v[78:81], v[56:59]
	s_waitcnt lgkmcnt(1)
	v_mfma_f32_16x16x32_bf16 v[52:55], v[124:127], v[78:81], v[52:55]
	s_waitcnt lgkmcnt(0)
	v_mfma_f32_16x16x32_bf16 v[48:51], v[128:131], v[78:81], v[48:51]
	v_mfma_f32_16x16x32_bf16 v[44:47], v[100:103], v[88:91], v[44:47]
	v_mfma_f32_16x16x32_bf16 v[40:43], v[120:123], v[88:91], v[40:43]
	v_mfma_f32_16x16x32_bf16 v[36:39], v[124:127], v[88:91], v[36:39]
	v_mfma_f32_16x16x32_bf16 v[32:35], v[128:131], v[88:91], v[32:35]
	v_mfma_f32_16x16x32_bf16 v[28:31], v[100:103], v[92:95], v[28:31]
	v_mfma_f32_16x16x32_bf16 v[24:27], v[120:123], v[92:95], v[24:27]
	v_mfma_f32_16x16x32_bf16 v[20:23], v[124:127], v[92:95], v[20:23]
	v_mfma_f32_16x16x32_bf16 v[16:19], v[128:131], v[92:95], v[16:19]
	v_mfma_f32_16x16x32_bf16 v[12:15], v[100:103], v[96:99], v[12:15]
	v_mfma_f32_16x16x32_bf16 v[8:11], v[120:123], v[96:99], v[8:11]
	v_mfma_f32_16x16x32_bf16 v[4:7], v[124:127], v[96:99], v[4:7]
	v_mfma_f32_16x16x32_bf16 v[0:3], v[128:131], v[96:99], v[0:3]
	s_setprio 0
	v_add_u32_e32 v96, v132, v87
	v_add_u32_e32 v128, v133, v87
	ds_read_b128 v[78:81], v96
	ds_read_b128 v[88:91], v96 offset:2048
	ds_read_b128 v[92:95], v96 offset:4096
	ds_read_b128 v[96:99], v96 offset:6144
	ds_read_b128 v[100:103], v128 offset:32768
	ds_read_b128 v[120:123], v128 offset:34816
	ds_read_b128 v[124:127], v128 offset:36864
	ds_read_b128 v[128:131], v128 offset:38912
	s_setprio 1
	s_waitcnt lgkmcnt(3)
	v_mfma_f32_16x16x32_bf16 v[60:63], v[100:103], v[78:81], v[60:63]
	s_waitcnt lgkmcnt(2)
	v_mfma_f32_16x16x32_bf16 v[56:59], v[120:123], v[78:81], v[56:59]
	s_waitcnt lgkmcnt(1)
	v_mfma_f32_16x16x32_bf16 v[52:55], v[124:127], v[78:81], v[52:55]
	s_waitcnt lgkmcnt(0)
	v_mfma_f32_16x16x32_bf16 v[48:51], v[128:131], v[78:81], v[48:51]
	v_mfma_f32_16x16x32_bf16 v[44:47], v[100:103], v[88:91], v[44:47]
	v_mfma_f32_16x16x32_bf16 v[40:43], v[120:123], v[88:91], v[40:43]
	v_mfma_f32_16x16x32_bf16 v[36:39], v[124:127], v[88:91], v[36:39]
	v_mfma_f32_16x16x32_bf16 v[32:35], v[128:131], v[88:91], v[32:35]
	v_mfma_f32_16x16x32_bf16 v[28:31], v[100:103], v[92:95], v[28:31]
	v_mfma_f32_16x16x32_bf16 v[24:27], v[120:123], v[92:95], v[24:27]
	v_mfma_f32_16x16x32_bf16 v[20:23], v[124:127], v[92:95], v[20:23]
	v_mfma_f32_16x16x32_bf16 v[16:19], v[128:131], v[92:95], v[16:19]
	v_mfma_f32_16x16x32_bf16 v[12:15], v[100:103], v[96:99], v[12:15]
	v_mfma_f32_16x16x32_bf16 v[8:11], v[120:123], v[96:99], v[8:11]
	v_mfma_f32_16x16x32_bf16 v[4:7], v[124:127], v[96:99], v[4:7]
	v_mfma_f32_16x16x32_bf16 v[0:3], v[128:131], v[96:99], v[0:3]
	s_setprio 0
	s_lshl_b32 s1, s25, 3
	s_lshl_b32 s8, s11, 1
	s_or_b32 s1, s8, s1
	s_or_b32 s1, s1, s13
	s_lshl_b32 s1, s1, 4
	s_or_b32 s8, s1, s24
	s_ashr_i32 s9, s8, 31
	s_lshl_b64 s[8:9], s[8:9], 18
	s_add_u32 s8, s52, s8
	v_add_lshl_u32 v78, s10, v71, 8
	s_addc_u32 s9, s53, s9
	v_or_b32_e32 v80, s0, v85
	v_ashrrev_i32_e32 v79, 31, v78
	v_lshl_add_u64 v[78:79], v[78:79], 1, s[8:9]
	v_cvt_pk_bf16_f32 v60, v60, v61
	v_cvt_pk_bf16_f32 v61, v62, v63
	v_lshlrev_b32_e32 v62, 1, v80
	v_mov_b32_e32 v63, v69
	v_lshl_add_u64 v[80:81], v[78:79], 0, v[62:63]
	v_cvt_pk_bf16_f32 v48, v48, v49
	v_cvt_pk_bf16_f32 v49, v50, v51
	s_mov_b64 s[0:1], 0x2000
	s_waitcnt vmcnt(0)
	s_barrier
	global_store_dwordx2 v[80:81], v[48:49], off offset:96
	v_lshl_add_u64 v[48:49], v[78:79], 0, s[0:1]
	v_cvt_pk_bf16_f32 v44, v44, v45
	v_cvt_pk_bf16_f32 v45, v46, v47
	v_lshl_add_u64 v[46:47], v[48:49], 0, v[62:63]
	v_cvt_pk_bf16_f32 v40, v40, v41
	v_cvt_pk_bf16_f32 v41, v42, v43
	v_or_b32_e32 v42, 32, v62
	v_mov_b32_e32 v43, v69
	global_store_dwordx2 v[46:47], v[44:45], off
	v_lshl_add_u64 v[44:45], v[48:49], 0, v[42:43]
	v_cvt_pk_bf16_f32 v36, v36, v37
	v_cvt_pk_bf16_f32 v37, v38, v39
	v_or_b32_e32 v38, 64, v62
	v_mov_b32_e32 v39, v69
	global_store_dwordx2 v[44:45], v[40:41], off
	v_lshl_add_u64 v[40:41], v[48:49], 0, v[38:39]
	v_cvt_pk_bf16_f32 v32, v32, v33
	v_cvt_pk_bf16_f32 v33, v34, v35
	v_or_b32_e32 v34, 0x60, v62
	v_mov_b32_e32 v35, v69
	global_store_dwordx2 v[40:41], v[36:37], off
	v_lshl_add_u64 v[36:37], v[48:49], 0, v[34:35]
	s_mov_b64 s[0:1], 0x4000
	global_store_dwordx2 v[36:37], v[32:33], off
	v_lshl_add_u64 v[32:33], v[78:79], 0, s[0:1]
	v_cvt_pk_bf16_f32 v16, v16, v17
	v_cvt_pk_bf16_f32 v17, v18, v19
	v_lshl_add_u64 v[18:19], v[32:33], 0, v[34:35]
	s_mov_b64 s[0:1], 0x6000
	global_store_dwordx2 v[18:19], v[16:17], off
	v_lshl_add_u64 v[16:17], v[78:79], 0, s[0:1]
	v_readlane_b32 s0, v181, 50
	s_add_i32 s6, s6, s84
	s_add_i32 s12, s12, s0
	v_cvt_pk_bf16_f32 v56, v56, v57
	v_cvt_pk_bf16_f32 v57, v58, v59
	v_cvt_pk_bf16_f32 v52, v52, v53
	v_cvt_pk_bf16_f32 v53, v54, v55
	v_cvt_pk_bf16_f32 v28, v28, v29
	v_cvt_pk_bf16_f32 v29, v30, v31
	v_lshl_add_u64 v[30:31], v[32:33], 0, v[62:63]
	v_cvt_pk_bf16_f32 v24, v24, v25
	v_cvt_pk_bf16_f32 v25, v26, v27
	v_lshl_add_u64 v[26:27], v[32:33], 0, v[42:43]
	v_cvt_pk_bf16_f32 v20, v20, v21
	v_cvt_pk_bf16_f32 v21, v22, v23
	v_lshl_add_u64 v[22:23], v[32:33], 0, v[38:39]
	v_cvt_pk_bf16_f32 v12, v12, v13
	v_cvt_pk_bf16_f32 v13, v14, v15
	v_lshl_add_u64 v[14:15], v[16:17], 0, v[62:63]
	v_cvt_pk_bf16_f32 v8, v8, v9
	v_cvt_pk_bf16_f32 v9, v10, v11
	v_lshl_add_u64 v[10:11], v[16:17], 0, v[42:43]
	v_cvt_pk_bf16_f32 v4, v4, v5
	v_cvt_pk_bf16_f32 v5, v6, v7
	v_lshl_add_u64 v[6:7], v[16:17], 0, v[38:39]
	v_cvt_pk_bf16_f32 v0, v0, v1
	v_cvt_pk_bf16_f32 v1, v2, v3
	v_lshl_add_u64 v[2:3], v[16:17], 0, v[34:35]
	s_cmpk_lt_i32 s6, 0x800
	global_store_dwordx2 v[80:81], v[60:61], off
	global_store_dwordx2 v[80:81], v[56:57], off offset:32
	global_store_dwordx2 v[80:81], v[52:53], off offset:64
	global_store_dwordx2 v[30:31], v[28:29], off
	global_store_dwordx2 v[26:27], v[24:25], off
	global_store_dwordx2 v[22:23], v[20:21], off
	global_store_dwordx2 v[14:15], v[12:13], off
	global_store_dwordx2 v[10:11], v[8:9], off
	global_store_dwordx2 v[6:7], v[4:5], off
	global_store_dwordx2 v[2:3], v[0:1], off
	s_cbranch_scc1 .LBB0_1234
	v_readlane_b32 s50, v180, 0
	s_mov_b32 s18, 0x42ce8ed0
	s_mov_b32 s19, 0xc2b17218
	s_mov_b32 s48, s5
	v_readlane_b32 s51, v180, 1

.LBB0_1487:
	s_setprio 3
	s_and_b32 s6, s0, 0x2000
	s_xor_b32 s8, s6, 0x2000
	s_lshl_b32 s101, s8, 1
	s_add_u32 s101, s101, s100
	s_add_u32 m0, s101, 0x0
	s_nop 0
	global_load_lds_dwordx4 v[184:185], off
	s_add_u32 m0, s101, 0x1000
	v_lshl_add_u64 v[184:185], v[184:185], 0, vcc
	global_load_lds_dwordx4 v[186:187], off
	s_add_u32 m0, s101, 0x2000
	v_lshl_add_u64 v[186:187], v[186:187], 0, vcc
	global_load_lds_dwordx4 v[188:189], off
	s_add_u32 m0, s101, 0x3000
	v_lshl_add_u64 v[188:189], v[188:189], 0, vcc
	global_load_lds_dwordx4 v[190:191], off
	s_add_u32 m0, s101, 0x8000
	v_lshl_add_u64 v[190:191], v[190:191], 0, vcc
	global_load_lds_dwordx4 v[192:193], off
	s_add_u32 m0, s101, 0x9000
	v_lshl_add_u64 v[192:193], v[192:193], 0, vcc
	global_load_lds_dwordx4 v[194:195], off
	s_add_u32 m0, s101, 0xa000
	v_lshl_add_u64 v[194:195], v[194:195], 0, vcc
	global_load_lds_dwordx4 v[196:197], off
	s_add_u32 m0, s101, 0xb000
	v_lshl_add_u64 v[196:197], v[196:197], 0, vcc
	global_load_lds_dwordx4 v[198:199], off
	v_lshl_add_u64 v[198:199], v[198:199], 0, vcc
	s_lshl_b32 s6, s6, 1
	v_add_u32_e32 v148, s6, v92
	v_add_u32_e32 v149, s6, v71
	v_add_u32_e32 v128, v148, v98
	v_add_u32_e32 v144, v149, v98
	ds_read_b128 v[100:103], v128
	ds_read_b128 v[120:123], v128 offset:2048
	ds_read_b128 v[124:127], v128 offset:4096
	ds_read_b128 v[128:131], v128 offset:6144
	ds_read_b128 v[132:135], v144 offset:32768
	ds_read_b128 v[136:139], v144 offset:34816
	ds_read_b128 v[140:143], v144 offset:36864
	ds_read_b128 v[144:147], v144 offset:38912
	v_add_u32_e32 v232, v148, v99
	v_add_u32_e32 v233, v149, v99
	ds_read_b128 v[200:203], v232
	ds_read_b128 v[204:207], v232 offset:2048
	ds_read_b128 v[208:211], v232 offset:4096
	ds_read_b128 v[212:215], v232 offset:6144
	ds_read_b128 v[216:219], v233 offset:32768
	ds_read_b128 v[220:223], v233 offset:34816
	ds_read_b128 v[224:227], v233 offset:36864
	ds_read_b128 v[228:231], v233 offset:38912
	s_setprio 1
	s_waitcnt lgkmcnt(11)
	v_mfma_f32_16x16x32_bf16 v[60:63], v[132:135], v[100:103], v[60:63]
	s_waitcnt lgkmcnt(10)
	v_mfma_f32_16x16x32_bf16 v[56:59], v[136:139], v[100:103], v[56:59]
	s_waitcnt lgkmcnt(9)
	v_mfma_f32_16x16x32_bf16 v[52:55], v[140:143], v[100:103], v[52:55]
	s_waitcnt lgkmcnt(8)
	v_mfma_f32_16x16x32_bf16 v[48:51], v[144:147], v[100:103], v[48:51]
	v_mfma_f32_16x16x32_bf16 v[44:47], v[132:135], v[120:123], v[44:47]
	v_mfma_f32_16x16x32_bf16 v[40:43], v[136:139], v[120:123], v[40:43]
	v_mfma_f32_16x16x32_bf16 v[36:39], v[140:143], v[120:123], v[36:39]
	v_mfma_f32_16x16x32_bf16 v[32:35], v[144:147], v[120:123], v[32:35]
	v_mfma_f32_16x16x32_bf16 v[28:31], v[132:135], v[124:127], v[28:31]
	v_mfma_f32_16x16x32_bf16 v[24:27], v[136:139], v[124:127], v[24:27]
	v_mfma_f32_16x16x32_bf16 v[20:23], v[140:143], v[124:127], v[20:23]
	v_mfma_f32_16x16x32_bf16 v[16:19], v[144:147], v[124:127], v[16:19]
	v_mfma_f32_16x16x32_bf16 v[12:15], v[132:135], v[128:131], v[12:15]
	v_mfma_f32_16x16x32_bf16 v[8:11], v[136:139], v[128:131], v[8:11]
	v_mfma_f32_16x16x32_bf16 v[4:7], v[140:143], v[128:131], v[4:7]
	v_mfma_f32_16x16x32_bf16 v[0:3], v[144:147], v[128:131], v[0:3]
	s_waitcnt lgkmcnt(3)
	v_mfma_f32_16x16x32_bf16 v[60:63], v[216:219], v[200:203], v[60:63]
	s_waitcnt lgkmcnt(2)
	v_mfma_f32_16x16x32_bf16 v[56:59], v[220:223], v[200:203], v[56:59]
	s_waitcnt lgkmcnt(1)
	v_mfma_f32_16x16x32_bf16 v[52:55], v[224:227], v[200:203], v[52:55]
	s_waitcnt lgkmcnt(0)
	v_mfma_f32_16x16x32_bf16 v[48:51], v[228:231], v[200:203], v[48:51]
	v_mfma_f32_16x16x32_bf16 v[44:47], v[216:219], v[204:207], v[44:47]
	v_mfma_f32_16x16x32_bf16 v[40:43], v[220:223], v[204:207], v[40:43]
	v_mfma_f32_16x16x32_bf16 v[36:39], v[224:227], v[204:207], v[36:39]
	v_mfma_f32_16x16x32_bf16 v[32:35], v[228:231], v[204:207], v[32:35]
	v_mfma_f32_16x16x32_bf16 v[28:31], v[216:219], v[208:211], v[28:31]
	v_mfma_f32_16x16x32_bf16 v[24:27], v[220:223], v[208:211], v[24:27]
	v_mfma_f32_16x16x32_bf16 v[20:23], v[224:227], v[208:211], v[20:23]
	v_mfma_f32_16x16x32_bf16 v[16:19], v[228:231], v[208:211], v[16:19]
	v_mfma_f32_16x16x32_bf16 v[12:15], v[216:219], v[212:215], v[12:15]
	v_mfma_f32_16x16x32_bf16 v[8:11], v[220:223], v[212:215], v[8:11]
	v_mfma_f32_16x16x32_bf16 v[4:7], v[224:227], v[212:215], v[4:7]
	v_mfma_f32_16x16x32_bf16 v[0:3], v[228:231], v[212:215], v[0:3]
	s_setprio 0
	s_waitcnt vmcnt(0)
	s_add_u32 s36, s36, 0x80
	s_addc_u32 s37, s37, 0
	s_addk_i32 s0, 0x2000
	s_cmpk_lg_i32 s36, 0xf80
	s_waitcnt vmcnt(0)
	s_barrier
	s_cbranch_scc1 .LBB0_1487
	ds_read_b128 v[88:91], v94 offset:16384
	ds_read_b128 v[100:103], v94 offset:18432
	ds_read_b128 v[120:123], v94 offset:20480
	ds_read_b128 v[124:127], v94 offset:22528
	ds_read_b128 v[128:131], v95 offset:49152
	ds_read_b128 v[132:135], v95 offset:51200
	ds_read_b128 v[136:139], v95 offset:53248
	ds_read_b128 v[140:143], v95 offset:55296
	s_setprio 1
	s_waitcnt lgkmcnt(3)
	v_mfma_f32_16x16x32_bf16 v[60:63], v[128:131], v[88:91], v[60:63]
	s_waitcnt lgkmcnt(2)
	v_mfma_f32_16x16x32_bf16 v[56:59], v[132:135], v[88:91], v[56:59]
	s_waitcnt lgkmcnt(1)
	v_mfma_f32_16x16x32_bf16 v[52:55], v[136:139], v[88:91], v[52:55]
	s_waitcnt lgkmcnt(0)
	v_mfma_f32_16x16x32_bf16 v[48:51], v[140:143], v[88:91], v[48:51]
	v_mfma_f32_16x16x32_bf16 v[40:43], v[132:135], v[100:103], v[40:43]
	v_mfma_f32_16x16x32_bf16 v[36:39], v[136:139], v[100:103], v[36:39]
	v_mfma_f32_16x16x32_bf16 v[32:35], v[140:143], v[100:103], v[32:35]
	v_mfma_f32_16x16x32_bf16 v[20:23], v[136:139], v[120:123], v[20:23]
	v_mfma_f32_16x16x32_bf16 v[16:19], v[140:143], v[120:123], v[16:19]
	v_mfma_f32_16x16x32_bf16 v[0:3], v[140:143], v[124:127], v[0:3]
	v_mfma_f32_16x16x32_bf16 v[88:91], v[128:131], v[100:103], v[44:47]
	v_mfma_f32_16x16x32_bf16 v[100:103], v[128:131], v[120:123], v[28:31]
	v_mfma_f32_16x16x32_bf16 v[144:147], v[132:135], v[120:123], v[24:27]
	v_mfma_f32_16x16x32_bf16 v[120:123], v[128:131], v[124:127], v[12:15]
	v_mfma_f32_16x16x32_bf16 v[128:131], v[132:135], v[124:127], v[8:11]
	v_mfma_f32_16x16x32_bf16 v[132:135], v[136:139], v[124:127], v[4:7]
	s_setprio 0
	s_nop 1
	ds_read_b128 v[4:7], v96 offset:16384
	ds_read_b128 v[8:11], v96 offset:18432
	ds_read_b128 v[124:127], v96 offset:20480
	ds_read_b128 v[136:139], v96 offset:22528
	ds_read_b128 v[140:143], v97 offset:49152
	ds_read_b128 v[148:151], v97 offset:51200
	ds_read_b128 v[152:155], v97 offset:53248
	ds_read_b128 v[156:159], v97 offset:55296
	s_setprio 1
	s_waitcnt lgkmcnt(3)
	v_mfma_f32_16x16x32_bf16 v[60:63], v[140:143], v[4:7], v[60:63]
	s_waitcnt lgkmcnt(2)
	v_mfma_f32_16x16x32_bf16 v[44:47], v[148:151], v[4:7], v[56:59]
	s_waitcnt lgkmcnt(1)
	v_mfma_f32_16x16x32_bf16 v[28:31], v[152:155], v[4:7], v[52:55]
	s_waitcnt lgkmcnt(0)
	v_mfma_f32_16x16x32_bf16 v[12:15], v[156:159], v[4:7], v[48:51]
	v_mfma_f32_16x16x32_bf16 v[56:59], v[140:143], v[8:11], v[88:91]
	v_mfma_f32_16x16x32_bf16 v[40:43], v[148:151], v[8:11], v[40:43]
	v_mfma_f32_16x16x32_bf16 v[24:27], v[152:155], v[8:11], v[36:39]
	v_mfma_f32_16x16x32_bf16 v[8:11], v[156:159], v[8:11], v[32:35]
	v_mfma_f32_16x16x32_bf16 v[52:55], v[140:143], v[124:127], v[100:103]
	v_mfma_f32_16x16x32_bf16 v[36:39], v[148:151], v[124:127], v[144:147]
	v_mfma_f32_16x16x32_bf16 v[20:23], v[152:155], v[124:127], v[20:23]
	v_mfma_f32_16x16x32_bf16 v[4:7], v[156:159], v[124:127], v[16:19]
	v_mfma_f32_16x16x32_bf16 v[48:51], v[140:143], v[136:139], v[120:123]
	v_mfma_f32_16x16x32_bf16 v[32:35], v[148:151], v[136:139], v[128:131]
	v_mfma_f32_16x16x32_bf16 v[16:19], v[152:155], v[136:139], v[132:135]
	v_mfma_f32_16x16x32_bf16 v[0:3], v[156:159], v[136:139], v[0:3]
	s_setprio 0
	s_waitcnt vmcnt(0)
	s_cmpk_gt_i32 s1, 0x7f
	s_barrier
	s_cbranch_scc0 .LBB0_1490
	s_add_i32 s0, s24, 0xffffc000
	s_lshr_b32 s0, s0, 8
	v_readlane_b32 s6, v180, 24
	s_add_i32 s6, s0, s6
	s_and_b32 s10, s24, 0x80
	s_lshl_b64 s[8:9], s[6:7], 8
	v_readlane_b32 s36, v182, 19
	s_or_b32 s8, s8, s10
	s_mov_b64 s[10:11], 0
	v_readlane_b32 s37, v182, 20
	s_branch .LBB0_1491

.LBB0_1498:
	s_setprio 3
	s_and_b32 s10, s6, 0x2000
	s_xor_b32 s8, s10, 0x2000
	s_lshl_b32 s101, s8, 1
	s_add_u32 s101, s101, s100
	s_add_u32 m0, s101, 0x0
	s_nop 0
	global_load_lds_dwordx4 v[184:185], off
	s_add_u32 m0, s101, 0x1000
	v_lshl_add_u64 v[184:185], v[184:185], 0, vcc
	global_load_lds_dwordx4 v[186:187], off
	s_add_u32 m0, s101, 0x2000
	v_lshl_add_u64 v[186:187], v[186:187], 0, vcc
	global_load_lds_dwordx4 v[188:189], off
	s_add_u32 m0, s101, 0x3000
	v_lshl_add_u64 v[188:189], v[188:189], 0, vcc
	global_load_lds_dwordx4 v[190:191], off
	s_add_u32 m0, s101, 0x8000
	v_lshl_add_u64 v[190:191], v[190:191], 0, vcc
	global_load_lds_dwordx4 v[192:193], off
	s_add_u32 m0, s101, 0x9000
	v_lshl_add_u64 v[192:193], v[192:193], 0, vcc
	global_load_lds_dwordx4 v[194:195], off
	s_add_u32 m0, s101, 0xa000
	v_lshl_add_u64 v[194:195], v[194:195], 0, vcc
	global_load_lds_dwordx4 v[196:197], off
	s_add_u32 m0, s101, 0xb000
	v_lshl_add_u64 v[196:197], v[196:197], 0, vcc
	global_load_lds_dwordx4 v[198:199], off
	v_lshl_add_u64 v[198:199], v[198:199], 0, vcc
	s_lshl_b32 s8, s10, 1
	v_add_u32_e32 v68, s8, v84
	v_add_u32_e32 v140, s8, v83
	v_add_u32_e32 v120, v68, v90
	v_add_u32_e32 v136, v140, v90
	ds_read_b128 v[92:95], v120
	ds_read_b128 v[96:99], v120 offset:2048
	ds_read_b128 v[100:103], v120 offset:4096
	ds_read_b128 v[120:123], v120 offset:6144
	ds_read_b128 v[124:127], v136 offset:32768
	ds_read_b128 v[128:131], v136 offset:34816
	ds_read_b128 v[132:135], v136 offset:36864
	ds_read_b128 v[136:139], v136 offset:38912
	v_add_u32_e32 v68, v68, v91
	ds_read_b128 v[200:203], v68
	ds_read_b128 v[204:207], v68 offset:2048
	ds_read_b128 v[208:211], v68 offset:4096
	ds_read_b128 v[212:215], v68 offset:6144
	v_add_u32_e32 v68, v140, v91
	ds_read_b128 v[216:219], v68 offset:32768
	ds_read_b128 v[220:223], v68 offset:34816
	ds_read_b128 v[224:227], v68 offset:36864
	ds_read_b128 v[228:231], v68 offset:38912
	s_setprio 1
	s_waitcnt lgkmcnt(11)
	v_mfma_f32_16x16x32_bf16 v[60:63], v[124:127], v[92:95], v[60:63]
	s_waitcnt lgkmcnt(10)
	v_mfma_f32_16x16x32_bf16 v[56:59], v[128:131], v[92:95], v[56:59]
	s_waitcnt lgkmcnt(9)
	v_mfma_f32_16x16x32_bf16 v[52:55], v[132:135], v[92:95], v[52:55]
	s_waitcnt lgkmcnt(8)
	v_mfma_f32_16x16x32_bf16 v[48:51], v[136:139], v[92:95], v[48:51]
	v_mfma_f32_16x16x32_bf16 v[44:47], v[124:127], v[96:99], v[44:47]
	v_mfma_f32_16x16x32_bf16 v[40:43], v[128:131], v[96:99], v[40:43]
	v_mfma_f32_16x16x32_bf16 v[36:39], v[132:135], v[96:99], v[36:39]
	v_mfma_f32_16x16x32_bf16 v[32:35], v[136:139], v[96:99], v[32:35]
	v_mfma_f32_16x16x32_bf16 v[28:31], v[124:127], v[100:103], v[28:31]
	v_mfma_f32_16x16x32_bf16 v[24:27], v[128:131], v[100:103], v[24:27]
	v_mfma_f32_16x16x32_bf16 v[20:23], v[132:135], v[100:103], v[20:23]
	v_mfma_f32_16x16x32_bf16 v[16:19], v[136:139], v[100:103], v[16:19]
	v_mfma_f32_16x16x32_bf16 v[12:15], v[124:127], v[120:123], v[12:15]
	v_mfma_f32_16x16x32_bf16 v[8:11], v[128:131], v[120:123], v[8:11]
	v_mfma_f32_16x16x32_bf16 v[4:7], v[132:135], v[120:123], v[4:7]
	v_mfma_f32_16x16x32_bf16 v[0:3], v[136:139], v[120:123], v[0:3]
	s_waitcnt lgkmcnt(3)
	v_mfma_f32_16x16x32_bf16 v[60:63], v[216:219], v[200:203], v[60:63]
	s_waitcnt lgkmcnt(2)
	v_mfma_f32_16x16x32_bf16 v[56:59], v[220:223], v[200:203], v[56:59]
	s_waitcnt lgkmcnt(1)
	v_mfma_f32_16x16x32_bf16 v[52:55], v[224:227], v[200:203], v[52:55]
	s_waitcnt lgkmcnt(0)
	v_mfma_f32_16x16x32_bf16 v[48:51], v[228:231], v[200:203], v[48:51]
	v_mfma_f32_16x16x32_bf16 v[44:47], v[216:219], v[204:207], v[44:47]
	v_mfma_f32_16x16x32_bf16 v[40:43], v[220:223], v[204:207], v[40:43]
	v_mfma_f32_16x16x32_bf16 v[36:39], v[224:227], v[204:207], v[36:39]
	v_mfma_f32_16x16x32_bf16 v[32:35], v[228:231], v[204:207], v[32:35]
	v_mfma_f32_16x16x32_bf16 v[28:31], v[216:219], v[208:211], v[28:31]
	v_mfma_f32_16x16x32_bf16 v[24:27], v[220:223], v[208:211], v[24:27]
	v_mfma_f32_16x16x32_bf16 v[20:23], v[224:227], v[208:211], v[20:23]
	v_mfma_f32_16x16x32_bf16 v[16:19], v[228:231], v[208:211], v[16:19]
	v_mfma_f32_16x16x32_bf16 v[12:15], v[216:219], v[212:215], v[12:15]
	v_mfma_f32_16x16x32_bf16 v[8:11], v[220:223], v[212:215], v[8:11]
	v_mfma_f32_16x16x32_bf16 v[4:7], v[224:227], v[212:215], v[4:7]
	v_mfma_f32_16x16x32_bf16 v[0:3], v[228:231], v[212:215], v[0:3]
	s_setprio 0
	s_addk_i32 s6, 0x2000
	s_waitcnt vmcnt(0)
	s_add_u32 s36, s36, 0x80
	s_addc_u32 s37, s37, 0
	s_cmpk_lg_i32 s36, 0x780
	s_waitcnt vmcnt(0)
	s_barrier
	s_cbranch_scc1 .LBB0_1498
	ds_read_b128 v[78:81], v85 offset:55296
	ds_read_b128 v[92:95], v85 offset:53248
	ds_read_b128 v[96:99], v85 offset:51200
	ds_read_b128 v[100:103], v85 offset:49152
	ds_read_b128 v[120:123], v86 offset:22528
	ds_read_b128 v[124:127], v86 offset:20480
	ds_read_b128 v[128:131], v86 offset:18432
	ds_read_b128 v[132:135], v86 offset:16384
	s_setprio 1
	s_waitcnt lgkmcnt(0)
	v_mfma_f32_16x16x32_bf16 v[60:63], v[100:103], v[132:135], v[60:63]
	v_mfma_f32_16x16x32_bf16 v[56:59], v[96:99], v[132:135], v[56:59]
	v_mfma_f32_16x16x32_bf16 v[52:55], v[92:95], v[132:135], v[52:55]
	v_mfma_f32_16x16x32_bf16 v[48:51], v[78:81], v[132:135], v[48:51]
	v_mfma_f32_16x16x32_bf16 v[44:47], v[100:103], v[128:131], v[44:47]
	v_mfma_f32_16x16x32_bf16 v[40:43], v[96:99], v[128:131], v[40:43]
	v_mfma_f32_16x16x32_bf16 v[36:39], v[92:95], v[128:131], v[36:39]
	v_mfma_f32_16x16x32_bf16 v[32:35], v[78:81], v[128:131], v[32:35]
	v_mfma_f32_16x16x32_bf16 v[28:31], v[100:103], v[124:127], v[28:31]
	v_mfma_f32_16x16x32_bf16 v[24:27], v[96:99], v[124:127], v[24:27]
	v_mfma_f32_16x16x32_bf16 v[20:23], v[92:95], v[124:127], v[20:23]
	v_mfma_f32_16x16x32_bf16 v[16:19], v[78:81], v[124:127], v[16:19]
	v_mfma_f32_16x16x32_bf16 v[12:15], v[100:103], v[120:123], v[12:15]
	v_mfma_f32_16x16x32_bf16 v[8:11], v[96:99], v[120:123], v[8:11]
	v_mfma_f32_16x16x32_bf16 v[4:7], v[92:95], v[120:123], v[4:7]
	v_mfma_f32_16x16x32_bf16 v[0:3], v[78:81], v[120:123], v[0:3]
	s_setprio 0
	ds_read_b128 v[78:81], v87 offset:16384
	ds_read_b128 v[92:95], v87 offset:18432
	ds_read_b128 v[96:99], v87 offset:20480
	ds_read_b128 v[100:103], v87 offset:22528
	ds_read_b128 v[120:123], v88 offset:49152
	ds_read_b128 v[124:127], v88 offset:51200
	ds_read_b128 v[128:131], v88 offset:53248
	ds_read_b128 v[132:135], v88 offset:55296
	s_setprio 1
	s_waitcnt lgkmcnt(3)
	v_mfma_f32_16x16x32_bf16 v[60:63], v[120:123], v[78:81], v[60:63]
	s_waitcnt lgkmcnt(2)
	v_mfma_f32_16x16x32_bf16 v[56:59], v[124:127], v[78:81], v[56:59]
	s_waitcnt lgkmcnt(1)
	v_mfma_f32_16x16x32_bf16 v[52:55], v[128:131], v[78:81], v[52:55]
	s_waitcnt lgkmcnt(0)
	v_mfma_f32_16x16x32_bf16 v[48:51], v[132:135], v[78:81], v[48:51]
	v_mfma_f32_16x16x32_bf16 v[44:47], v[120:123], v[92:95], v[44:47]
	v_mfma_f32_16x16x32_bf16 v[40:43], v[124:127], v[92:95], v[40:43]
	v_mfma_f32_16x16x32_bf16 v[36:39], v[128:131], v[92:95], v[36:39]
	v_mfma_f32_16x16x32_bf16 v[32:35], v[132:135], v[92:95], v[32:35]
	v_mfma_f32_16x16x32_bf16 v[28:31], v[120:123], v[96:99], v[28:31]
	v_mfma_f32_16x16x32_bf16 v[24:27], v[124:127], v[96:99], v[24:27]
	v_mfma_f32_16x16x32_bf16 v[20:23], v[128:131], v[96:99], v[20:23]
	v_mfma_f32_16x16x32_bf16 v[16:19], v[132:135], v[96:99], v[16:19]
	v_mfma_f32_16x16x32_bf16 v[12:15], v[120:123], v[100:103], v[12:15]
	v_mfma_f32_16x16x32_bf16 v[8:11], v[124:127], v[100:103], v[8:11]
	v_mfma_f32_16x16x32_bf16 v[4:7], v[128:131], v[100:103], v[4:7]
	v_mfma_f32_16x16x32_bf16 v[0:3], v[132:135], v[100:103], v[0:3]
	s_setprio 0
	s_ashr_i32 s1, s1, 4
	s_mul_hi_i32 s6, s1, 0x4200000
	s_mul_i32 s1, s1, 0x4200000
	s_add_u32 s8, s90, s1
	v_add_u32_e32 v78, s20, v71
	s_addc_u32 s9, s91, s6
	s_and_b32 s1, s24, 0x780
	v_ashrrev_i32_e32 v79, 31, v78
	v_or_b32_e32 v68, s1, v89
	v_lshlrev_b64 v[80:81], 12, v[78:79]
	v_lshl_add_u64 v[80:81], s[8:9], 0, v[80:81]
	v_lshlrev_b32_e32 v68, 1, v68
	v_cvt_pk_bf16_f32 v60, v60, v61
	v_cvt_pk_bf16_f32 v61, v62, v63
	v_lshl_add_u64 v[62:63], v[80:81], 0, v[68:69]
	v_cvt_pk_bf16_f32 v48, v48, v49
	v_cvt_pk_bf16_f32 v49, v50, v51
	s_waitcnt vmcnt(0)
	s_barrier
	global_store_dwordx2 v[62:63], v[48:49], off offset:96
	v_or_b32_e32 v48, 16, v78
	v_ashrrev_i32_e32 v49, 31, v48
	v_lshlrev_b64 v[48:49], 12, v[48:49]
	v_lshl_add_u64 v[48:49], s[8:9], 0, v[48:49]
	v_cvt_pk_bf16_f32 v44, v44, v45
	v_cvt_pk_bf16_f32 v45, v46, v47
	v_lshl_add_u64 v[46:47], v[48:49], 0, v[68:69]
	v_cvt_pk_bf16_f32 v32, v32, v33
	v_cvt_pk_bf16_f32 v33, v34, v35
	global_store_dwordx2 v[46:47], v[32:33], off offset:96
	v_or_b32_e32 v32, 32, v78
	v_ashrrev_i32_e32 v33, 31, v32
	v_lshlrev_b64 v[32:33], 12, v[32:33]
	v_lshl_add_u64 v[32:33], s[8:9], 0, v[32:33]
	v_cvt_pk_bf16_f32 v28, v28, v29
	v_cvt_pk_bf16_f32 v29, v30, v31
	v_lshl_add_u64 v[30:31], v[32:33], 0, v[68:69]
	v_cvt_pk_bf16_f32 v16, v16, v17
	v_cvt_pk_bf16_f32 v17, v18, v19
	global_store_dwordx2 v[30:31], v[16:17], off offset:96
	v_or_b32_e32 v16, 48, v78
	v_ashrrev_i32_e32 v17, 31, v16
	v_lshlrev_b64 v[16:17], 12, v[16:17]
	v_lshl_add_u64 v[16:17], s[8:9], 0, v[16:17]
	s_add_i32 s0, s0, s84
	v_cvt_pk_bf16_f32 v56, v56, v57
	v_cvt_pk_bf16_f32 v57, v58, v59
	v_cvt_pk_bf16_f32 v52, v52, v53
	v_cvt_pk_bf16_f32 v53, v54, v55
	v_cvt_pk_bf16_f32 v40, v40, v41
	v_cvt_pk_bf16_f32 v41, v42, v43
	v_cvt_pk_bf16_f32 v36, v36, v37
	v_cvt_pk_bf16_f32 v37, v38, v39
	v_cvt_pk_bf16_f32 v24, v24, v25
	v_cvt_pk_bf16_f32 v25, v26, v27
	v_cvt_pk_bf16_f32 v20, v20, v21
	v_cvt_pk_bf16_f32 v21, v22, v23
	v_cvt_pk_bf16_f32 v12, v12, v13
	v_cvt_pk_bf16_f32 v13, v14, v15
	v_lshl_add_u64 v[14:15], v[16:17], 0, v[68:69]
	v_cvt_pk_bf16_f32 v8, v8, v9
	v_cvt_pk_bf16_f32 v9, v10, v11
	v_cvt_pk_bf16_f32 v4, v4, v5
	v_cvt_pk_bf16_f32 v5, v6, v7
	v_cvt_pk_bf16_f32 v0, v0, v1
	v_cvt_pk_bf16_f32 v1, v2, v3
	s_cmpk_lt_i32 s0, 0x18c0
	global_store_dwordx2 v[62:63], v[60:61], off
	global_store_dwordx2 v[62:63], v[56:57], off offset:32
	global_store_dwordx2 v[62:63], v[52:53], off offset:64
	global_store_dwordx2 v[46:47], v[44:45], off
	global_store_dwordx2 v[46:47], v[40:41], off offset:32
	global_store_dwordx2 v[46:47], v[36:37], off offset:64
	global_store_dwordx2 v[30:31], v[28:29], off
	global_store_dwordx2 v[30:31], v[24:25], off offset:32
	global_store_dwordx2 v[30:31], v[20:21], off offset:64
	global_store_dwordx2 v[14:15], v[12:13], off
	global_store_dwordx2 v[14:15], v[8:9], off offset:32
	global_store_dwordx2 v[14:15], v[4:5], off offset:64
	global_store_dwordx2 v[14:15], v[0:1], off offset:96
	s_cbranch_scc1 .LBB0_1497

.LBB0_1707:
	s_setprio 3
	s_and_b32 s6, s0, 0x2000
	s_xor_b32 s8, s6, 0x2000
	s_lshl_b32 s101, s8, 1
	s_add_u32 s101, s101, s100
	s_add_u32 m0, s101, 0x0
	s_nop 0
	global_load_lds_dwordx4 v[184:185], off
	s_add_u32 m0, s101, 0x1000
	v_lshl_add_u64 v[184:185], v[184:185], 0, vcc
	global_load_lds_dwordx4 v[186:187], off
	s_add_u32 m0, s101, 0x2000
	v_lshl_add_u64 v[186:187], v[186:187], 0, vcc
	global_load_lds_dwordx4 v[188:189], off
	s_add_u32 m0, s101, 0x3000
	v_lshl_add_u64 v[188:189], v[188:189], 0, vcc
	global_load_lds_dwordx4 v[190:191], off
	s_add_u32 m0, s101, 0x8000
	v_lshl_add_u64 v[190:191], v[190:191], 0, vcc
	global_load_lds_dwordx4 v[192:193], off
	s_add_u32 m0, s101, 0x9000
	v_lshl_add_u64 v[192:193], v[192:193], 0, vcc
	global_load_lds_dwordx4 v[194:195], off
	s_add_u32 m0, s101, 0xa000
	v_lshl_add_u64 v[194:195], v[194:195], 0, vcc
	global_load_lds_dwordx4 v[196:197], off
	s_add_u32 m0, s101, 0xb000
	v_lshl_add_u64 v[196:197], v[196:197], 0, vcc
	global_load_lds_dwordx4 v[198:199], off
	v_lshl_add_u64 v[198:199], v[198:199], 0, vcc
	s_lshl_b32 s6, s6, 1
	v_add_u32_e32 v102, s6, v90
	v_add_u32_e32 v103, s6, v71
	v_add_u32_e32 v128, v102, v96
	v_add_u32_e32 v144, v103, v96
	ds_read_b128 v[98:101], v128
	ds_read_b128 v[120:123], v128 offset:2048
	ds_read_b128 v[124:127], v128 offset:4096
	ds_read_b128 v[128:131], v128 offset:6144
	ds_read_b128 v[132:135], v144 offset:32768
	ds_read_b128 v[136:139], v144 offset:34816
	ds_read_b128 v[140:143], v144 offset:36864
	ds_read_b128 v[144:147], v144 offset:38912
	v_add_u32_e32 v102, v102, v97
	ds_read_b128 v[200:203], v102
	ds_read_b128 v[204:207], v102 offset:2048
	ds_read_b128 v[208:211], v102 offset:4096
	ds_read_b128 v[212:215], v102 offset:6144
	v_add_u32_e32 v102, v103, v97
	ds_read_b128 v[216:219], v102 offset:32768
	ds_read_b128 v[220:223], v102 offset:34816
	ds_read_b128 v[224:227], v102 offset:36864
	ds_read_b128 v[228:231], v102 offset:38912
	s_setprio 1
	s_waitcnt lgkmcnt(11)
	v_mfma_f32_16x16x32_bf16 v[60:63], v[132:135], v[98:101], v[60:63]
	s_waitcnt lgkmcnt(10)
	v_mfma_f32_16x16x32_bf16 v[56:59], v[136:139], v[98:101], v[56:59]
	s_waitcnt lgkmcnt(9)
	v_mfma_f32_16x16x32_bf16 v[52:55], v[140:143], v[98:101], v[52:55]
	s_waitcnt lgkmcnt(8)
	v_mfma_f32_16x16x32_bf16 v[48:51], v[144:147], v[98:101], v[48:51]
	v_mfma_f32_16x16x32_bf16 v[44:47], v[132:135], v[120:123], v[44:47]
	v_mfma_f32_16x16x32_bf16 v[40:43], v[136:139], v[120:123], v[40:43]
	v_mfma_f32_16x16x32_bf16 v[36:39], v[140:143], v[120:123], v[36:39]
	v_mfma_f32_16x16x32_bf16 v[32:35], v[144:147], v[120:123], v[32:35]
	v_mfma_f32_16x16x32_bf16 v[28:31], v[132:135], v[124:127], v[28:31]
	v_mfma_f32_16x16x32_bf16 v[24:27], v[136:139], v[124:127], v[24:27]
	v_mfma_f32_16x16x32_bf16 v[20:23], v[140:143], v[124:127], v[20:23]
	v_mfma_f32_16x16x32_bf16 v[16:19], v[144:147], v[124:127], v[16:19]
	v_mfma_f32_16x16x32_bf16 v[12:15], v[132:135], v[128:131], v[12:15]
	v_mfma_f32_16x16x32_bf16 v[8:11], v[136:139], v[128:131], v[8:11]
	v_mfma_f32_16x16x32_bf16 v[4:7], v[140:143], v[128:131], v[4:7]
	v_mfma_f32_16x16x32_bf16 v[0:3], v[144:147], v[128:131], v[0:3]
	s_waitcnt lgkmcnt(3)
	v_mfma_f32_16x16x32_bf16 v[60:63], v[216:219], v[200:203], v[60:63]
	s_waitcnt lgkmcnt(2)
	v_mfma_f32_16x16x32_bf16 v[56:59], v[220:223], v[200:203], v[56:59]
	s_waitcnt lgkmcnt(1)
	v_mfma_f32_16x16x32_bf16 v[52:55], v[224:227], v[200:203], v[52:55]
	s_waitcnt lgkmcnt(0)
	v_mfma_f32_16x16x32_bf16 v[48:51], v[228:231], v[200:203], v[48:51]
	v_mfma_f32_16x16x32_bf16 v[44:47], v[216:219], v[204:207], v[44:47]
	v_mfma_f32_16x16x32_bf16 v[40:43], v[220:223], v[204:207], v[40:43]
	v_mfma_f32_16x16x32_bf16 v[36:39], v[224:227], v[204:207], v[36:39]
	v_mfma_f32_16x16x32_bf16 v[32:35], v[228:231], v[204:207], v[32:35]
	v_mfma_f32_16x16x32_bf16 v[28:31], v[216:219], v[208:211], v[28:31]
	v_mfma_f32_16x16x32_bf16 v[24:27], v[220:223], v[208:211], v[24:27]
	v_mfma_f32_16x16x32_bf16 v[20:23], v[224:227], v[208:211], v[20:23]
	v_mfma_f32_16x16x32_bf16 v[16:19], v[228:231], v[208:211], v[16:19]
	v_mfma_f32_16x16x32_bf16 v[12:15], v[216:219], v[212:215], v[12:15]
	v_mfma_f32_16x16x32_bf16 v[8:11], v[220:223], v[212:215], v[8:11]
	v_mfma_f32_16x16x32_bf16 v[4:7], v[224:227], v[212:215], v[4:7]
	v_mfma_f32_16x16x32_bf16 v[0:3], v[228:231], v[212:215], v[0:3]
	s_setprio 0
	s_waitcnt vmcnt(0)
	s_add_u32 s36, s36, 0x80
	s_addc_u32 s37, s37, 0
	s_addk_i32 s0, 0x2000
	s_cmpk_lg_i32 s36, 0xf80
	s_waitcnt vmcnt(0)
	s_barrier
	s_cbranch_scc1 .LBB0_1707
	ds_read_b128 v[86:89], v92 offset:16384
	ds_read_b128 v[98:101], v92 offset:18432
	ds_read_b128 v[120:123], v92 offset:20480
	ds_read_b128 v[124:127], v92 offset:22528
	ds_read_b128 v[128:131], v93 offset:49152
	ds_read_b128 v[132:135], v93 offset:51200
	ds_read_b128 v[136:139], v93 offset:53248
	ds_read_b128 v[140:143], v93 offset:55296
	s_setprio 1
	s_waitcnt lgkmcnt(3)
	v_mfma_f32_16x16x32_bf16 v[60:63], v[128:131], v[86:89], v[60:63]
	s_waitcnt lgkmcnt(2)
	v_mfma_f32_16x16x32_bf16 v[56:59], v[132:135], v[86:89], v[56:59]
	s_waitcnt lgkmcnt(1)
	v_mfma_f32_16x16x32_bf16 v[52:55], v[136:139], v[86:89], v[52:55]
	s_waitcnt lgkmcnt(0)
	v_mfma_f32_16x16x32_bf16 v[48:51], v[140:143], v[86:89], v[48:51]
	v_mfma_f32_16x16x32_bf16 v[40:43], v[132:135], v[98:101], v[40:43]
	v_mfma_f32_16x16x32_bf16 v[36:39], v[136:139], v[98:101], v[36:39]
	v_mfma_f32_16x16x32_bf16 v[32:35], v[140:143], v[98:101], v[32:35]
	v_mfma_f32_16x16x32_bf16 v[20:23], v[136:139], v[120:123], v[20:23]
	v_mfma_f32_16x16x32_bf16 v[16:19], v[140:143], v[120:123], v[16:19]
	v_mfma_f32_16x16x32_bf16 v[0:3], v[140:143], v[124:127], v[0:3]
	v_mfma_f32_16x16x32_bf16 v[86:89], v[128:131], v[98:101], v[44:47]
	v_mfma_f32_16x16x32_bf16 v[98:101], v[128:131], v[120:123], v[28:31]
	v_mfma_f32_16x16x32_bf16 v[144:147], v[132:135], v[120:123], v[24:27]
	v_mfma_f32_16x16x32_bf16 v[120:123], v[128:131], v[124:127], v[12:15]
	v_mfma_f32_16x16x32_bf16 v[128:131], v[132:135], v[124:127], v[8:11]
	v_mfma_f32_16x16x32_bf16 v[132:135], v[136:139], v[124:127], v[4:7]
	s_setprio 0
	s_nop 1
	ds_read_b128 v[4:7], v94 offset:16384
	ds_read_b128 v[8:11], v94 offset:18432
	ds_read_b128 v[124:127], v94 offset:20480
	ds_read_b128 v[136:139], v94 offset:22528
	ds_read_b128 v[140:143], v95 offset:49152
	ds_read_b128 v[148:151], v95 offset:51200
	ds_read_b128 v[152:155], v95 offset:53248
	ds_read_b128 v[156:159], v95 offset:55296
	s_setprio 1
	s_waitcnt lgkmcnt(3)
	v_mfma_f32_16x16x32_bf16 v[60:63], v[140:143], v[4:7], v[60:63]
	s_waitcnt lgkmcnt(2)
	v_mfma_f32_16x16x32_bf16 v[44:47], v[148:151], v[4:7], v[56:59]
	s_waitcnt lgkmcnt(1)
	v_mfma_f32_16x16x32_bf16 v[28:31], v[152:155], v[4:7], v[52:55]
	s_waitcnt lgkmcnt(0)
	v_mfma_f32_16x16x32_bf16 v[12:15], v[156:159], v[4:7], v[48:51]
	v_mfma_f32_16x16x32_bf16 v[56:59], v[140:143], v[8:11], v[86:89]
	v_mfma_f32_16x16x32_bf16 v[40:43], v[148:151], v[8:11], v[40:43]
	v_mfma_f32_16x16x32_bf16 v[24:27], v[152:155], v[8:11], v[36:39]
	v_mfma_f32_16x16x32_bf16 v[8:11], v[156:159], v[8:11], v[32:35]
	v_mfma_f32_16x16x32_bf16 v[52:55], v[140:143], v[124:127], v[98:101]
	v_mfma_f32_16x16x32_bf16 v[36:39], v[148:151], v[124:127], v[144:147]
	v_mfma_f32_16x16x32_bf16 v[20:23], v[152:155], v[124:127], v[20:23]
	v_mfma_f32_16x16x32_bf16 v[4:7], v[156:159], v[124:127], v[16:19]
	v_mfma_f32_16x16x32_bf16 v[48:51], v[140:143], v[136:139], v[120:123]
	v_mfma_f32_16x16x32_bf16 v[32:35], v[148:151], v[136:139], v[128:131]
	v_mfma_f32_16x16x32_bf16 v[16:19], v[152:155], v[136:139], v[132:135]
	v_mfma_f32_16x16x32_bf16 v[0:3], v[156:159], v[136:139], v[0:3]
	s_setprio 0
	s_waitcnt vmcnt(0)
	s_cmpk_gt_i32 s1, 0x7f
	s_barrier
	s_cbranch_scc0 .LBB0_1710
	s_add_i32 s0, s24, 0xffffc000
	s_lshr_b32 s0, s0, 8
	v_readlane_b32 s6, v180, 24
	s_add_i32 s6, s0, s6
	s_and_b32 s10, s24, 0x80
	s_lshl_b64 s[8:9], s[6:7], 8
	v_readlane_b32 s36, v182, 19
	s_or_b32 s8, s8, s10
	s_mov_b64 s[10:11], 0
	v_readlane_b32 s37, v182, 20
	s_branch .LBB0_1711
